# gMLP items: all 41 global loads of an item issued up front (compiler issued them in three dependent batches)
# speedup vs baseline: 1.0086x; 1.0049x over previous
.LBB0_1177:
	v_mov_b32_e32 v0, v218
	s_or_b32 s30, s8, s44
	v_readfirstlane_b32 s28, v0
	s_ashr_i32 s8, s28, 2
	s_and_b32 s31, s8, -16
	v_bfe_u32 v66, v0, 4, 2
	s_add_i32 s8, s31, s30
	v_and_b32_e32 v88, 63, v0
	v_and_b32_e32 v89, 15, v0
	v_or_b32_e32 v2, s8, v66
	v_mov_b64_e32 v[0:1], s[42:43]
	v_mad_i64_i32 v[0:1], s[8:9], v2, s70, v[0:1]
	v_lshlrev_b32_e32 v32, 4, v89
	v_lshl_add_u64 v[0:1], v[0:1], 0, v[32:33]
	s_mov_b64 s[8:9], 0x400
	v_lshl_add_u64 v[6:7], v[0:1], 0, s[8:9]
	global_load_dwordx4 v[8:11], v[0:1], off offset:1024
	global_load_dwordx4 v[12:15], v[0:1], off offset:1280
	global_load_dwordx4 v[16:19], v[0:1], off offset:1536
	s_nop 0
	global_load_dwordx4 v[0:3], v[0:1], off offset:1792
	v_add_co_u32_e32 v116, vcc, 0x15000, v6
	s_nop 1
	v_addc_co_u32_e32 v117, vcc, 0, v7, vcc
	global_load_dwordx4 v[62:65], v[116:117], off
	global_load_dwordx4 v[58:61], v[116:117], off offset:256
	global_load_dwordx4 v[54:57], v[116:117], off offset:512
	global_load_dwordx4 v[50:53], v[116:117], off offset:768
	v_add_co_u32_e32 v116, vcc, 0x2a000, v6
	s_nop 1
	v_addc_co_u32_e32 v117, vcc, 0, v7, vcc
	global_load_dwordx4 v[46:49], v[116:117], off
	global_load_dwordx4 v[42:45], v[116:117], off offset:256
	global_load_dwordx4 v[38:41], v[116:117], off offset:512
	global_load_dwordx4 v[34:37], v[116:117], off offset:768
	v_add_co_u32_e32 v116, vcc, 0x3f000, v6
	s_nop 1
	v_addc_co_u32_e32 v117, vcc, 0, v7, vcc
	global_load_dwordx4 v[28:31], v[116:117], off
	global_load_dwordx4 v[24:27], v[116:117], off offset:256
	global_load_dwordx4 v[20:23], v[116:117], off offset:512
	global_load_dwordx4 v[118:121], v[116:117], off offset:768
	v_lshlrev_b32_e32 v122, 5, v89
	global_load_dwordx4 v[124:127], v122, s[14:15] offset:16
	global_load_dwordx4 v[128:131], v122, s[14:15]
	global_load_dwordx4 v[132:135], v122, s[16:17] offset:16
	global_load_dwordx4 v[136:139], v122, s[16:17]
	v_readlane_b32 s60, v252, 50
	v_readlane_b32 s61, v252, 51
	v_or_b32_e32 v158, s31, v89
	v_lshlrev_b32_e32 v159, 8, v158
	v_lshl_add_u32 v159, v66, 4, v159
	v_add_u32_e32 v160, s30, v158
	v_mul_lo_u32 v160, v160, s70
	v_lshl_add_u32 v160, v66, 3, v160
	v_add_u32_e32 v161, s2, v158
	v_lshlrev_b32_e32 v161, 2, v161
	global_load_dwordx4 v[140:143], v159, s[18:19]
	global_load_dwordx4 v[144:147], v159, s[18:19] offset:64
	global_load_dwordx4 v[148:151], v159, s[18:19] offset:128
	global_load_dwordx4 v[152:155], v159, s[18:19] offset:192
	global_load_dwordx2 v[164:165], v160, s[34:35]
	global_load_dwordx2 v[166:167], v160, s[34:35] offset:2048
	global_load_dwordx2 v[168:169], v160, s[34:35] offset:32
	global_load_dwordx2 v[170:171], v160, s[34:35] offset:2080
	global_load_dwordx2 v[172:173], v160, s[34:35] offset:64
	global_load_dwordx2 v[174:175], v160, s[34:35] offset:2112
	global_load_dwordx2 v[176:177], v160, s[34:35] offset:96
	global_load_dwordx2 v[178:179], v160, s[34:35] offset:2144
	global_load_dwordx2 v[180:181], v160, s[34:35] offset:128
	global_load_dwordx2 v[182:183], v160, s[34:35] offset:2176
	global_load_dwordx2 v[184:185], v160, s[34:35] offset:160
	global_load_dwordx2 v[186:187], v160, s[34:35] offset:2208
	global_load_dwordx2 v[188:189], v160, s[34:35] offset:192
	global_load_dwordx2 v[190:191], v160, s[34:35] offset:2240
	global_load_dwordx2 v[192:193], v160, s[34:35] offset:224
	global_load_dwordx2 v[194:195], v160, s[34:35] offset:2272
	global_load_dword v156, v161, s[60:61]
	v_and_b32_e32 v5, 64, v226
	v_add_u32_e32 v162, 64, v5
	v_lshlrev_b32_e32 v4, 3, v89
	s_xor_b64 s[20:21], s[10:11], -1
	s_cmp_lt_i32 s65, 2
	s_mov_b64 s[10:11], -1
	s_waitcnt vmcnt(40)
	v_lshlrev_b32_e32 v70, 16, v8
	v_and_b32_e32 v71, 0xffff0000, v8
	v_lshlrev_b32_e32 v72, 16, v9
	v_and_b32_e32 v73, 0xffff0000, v9
	v_lshlrev_b32_e32 v74, 16, v10
	v_and_b32_e32 v75, 0xffff0000, v10
	v_lshlrev_b32_e32 v76, 16, v11
	v_and_b32_e32 v77, 0xffff0000, v11
	v_add_f32_e32 v5, v70, v71
	v_add_f32_e32 v8, v72, v73
	v_add_f32_e32 v5, v5, v8
	v_add_f32_e32 v8, v74, v75
	v_add_f32_e32 v9, v76, v77
	v_add_f32_e32 v8, v8, v9
	v_add_f32_e32 v5, v5, v8
	v_mul_f32_e32 v8, v71, v71
	v_mul_f32_e32 v9, v73, v73
	v_fmac_f32_e32 v8, v70, v70
	v_fmac_f32_e32 v9, v72, v72
	v_add_f32_e32 v8, v8, v9
	v_mul_f32_e32 v9, v75, v75
	v_mul_f32_e32 v10, v77, v77
	v_fmac_f32_e32 v9, v74, v74
	v_fmac_f32_e32 v10, v76, v76
	v_add_f32_e32 v9, v9, v10
	s_waitcnt vmcnt(39)
	v_lshlrev_b32_e32 v78, 16, v12
	v_and_b32_e32 v79, 0xffff0000, v12
	v_lshlrev_b32_e32 v80, 16, v13
	v_and_b32_e32 v81, 0xffff0000, v13
	v_add_f32_e32 v8, v8, v9
	v_lshlrev_b32_e32 v82, 16, v14
	v_and_b32_e32 v83, 0xffff0000, v14
	v_lshlrev_b32_e32 v84, 16, v15
	v_and_b32_e32 v85, 0xffff0000, v15
	v_add_f32_e32 v9, v78, v79
	v_add_f32_e32 v10, v80, v81
	v_add_f32_e32 v9, v9, v10
	v_add_f32_e32 v10, v82, v83
	v_add_f32_e32 v11, v84, v85
	v_add_f32_e32 v10, v10, v11
	v_add_f32_e32 v5, 0, v5
	v_add_f32_e32 v9, v9, v10
	v_add_f32_e32 v5, v5, v9
	v_mul_f32_e32 v9, v79, v79
	v_mul_f32_e32 v10, v81, v81
	s_waitcnt vmcnt(37)
	v_lshlrev_b32_e32 v103, 16, v0
	v_and_b32_e32 v102, 0xffff0000, v0
	v_lshlrev_b32_e32 v101, 16, v1
	v_and_b32_e32 v100, 0xffff0000, v1
	v_fmac_f32_e32 v9, v78, v78
	v_fmac_f32_e32 v10, v80, v80
	v_lshlrev_b32_e32 v99, 16, v2
	v_and_b32_e32 v98, 0xffff0000, v2
	v_lshlrev_b32_e32 v97, 16, v3
	v_and_b32_e32 v96, 0xffff0000, v3
	v_add_f32_e32 v0, v103, v102
	v_add_f32_e32 v1, v101, v100
	v_add_f32_e32 v9, v9, v10
	v_mul_f32_e32 v10, v83, v83
	v_mul_f32_e32 v11, v85, v85
	v_add_f32_e32 v0, v0, v1
	v_add_f32_e32 v1, v99, v98
	v_add_f32_e32 v2, v97, v96
	v_fmac_f32_e32 v10, v82, v82
	v_fmac_f32_e32 v11, v84, v84
	v_add_f32_e32 v1, v1, v2
	v_add_f32_e32 v10, v10, v11
	v_add_f32_e32 v0, v0, v1
	v_mul_f32_e32 v1, v102, v102
	v_mul_f32_e32 v2, v100, v100
	v_add_f32_e32 v9, v9, v10
	v_lshlrev_b32_e32 v86, 16, v16
	v_and_b32_e32 v87, 0xffff0000, v16
	v_lshlrev_b32_e32 v90, 16, v17
	v_and_b32_e32 v91, 0xffff0000, v17
	v_fmac_f32_e32 v1, v103, v103
	v_fmac_f32_e32 v2, v101, v101
	v_add_f32_e32 v8, v8, v9
	v_lshlrev_b32_e32 v92, 16, v18
	v_and_b32_e32 v93, 0xffff0000, v18
	v_lshlrev_b32_e32 v94, 16, v19
	v_and_b32_e32 v95, 0xffff0000, v19
	v_add_f32_e32 v9, v86, v87
	v_add_f32_e32 v10, v90, v91
	v_add_f32_e32 v1, v1, v2
	v_mul_f32_e32 v2, v98, v98
	v_mul_f32_e32 v3, v96, v96
	v_add_f32_e32 v9, v9, v10
	v_add_f32_e32 v10, v92, v93
	v_add_f32_e32 v11, v94, v95
	v_fmac_f32_e32 v2, v99, v99
	v_fmac_f32_e32 v3, v97, v97
	v_add_f32_e32 v10, v10, v11
	v_add_f32_e32 v2, v2, v3
	v_add_f32_e32 v9, v9, v10
	v_add_f32_e32 v1, v1, v2
	v_xor_b32_e32 v2, 1, v226
	v_add_f32_e32 v5, v5, v9
	v_mul_f32_e32 v9, v87, v87
	v_mul_f32_e32 v10, v91, v91
	v_cmp_lt_i32_e32 vcc, v2, v162
	v_fmac_f32_e32 v9, v86, v86
	v_fmac_f32_e32 v10, v90, v90
	v_cndmask_b32_e32 v2, v226, v2, vcc
	v_add_f32_e32 v9, v9, v10
	v_mul_f32_e32 v10, v93, v93
	v_mul_f32_e32 v11, v95, v95
	v_add_f32_e32 v0, v5, v0
	v_lshlrev_b32_e32 v69, 2, v2
	v_fmac_f32_e32 v10, v92, v92
	v_fmac_f32_e32 v11, v94, v94
	ds_bpermute_b32 v2, v69, v0
	v_add_f32_e32 v10, v10, v11
	v_add_f32_e32 v9, v9, v10
	v_add_f32_e32 v8, v8, v9
	v_add_f32_e32 v1, v8, v1
	s_waitcnt lgkmcnt(0)
	v_add_f32_e32 v0, v0, v2
	ds_bpermute_b32 v2, v69, v1
	v_lshlrev_b32_e32 v12, 2, v4
	s_waitcnt lgkmcnt(0)
	v_add_f32_e32 v1, v1, v2
	v_xor_b32_e32 v2, 2, v226
	v_cmp_lt_i32_e32 vcc, v2, v162
	s_nop 1
	v_cndmask_b32_e32 v2, v226, v2, vcc
	v_lshlrev_b32_e32 v68, 2, v2
	ds_bpermute_b32 v2, v68, v0
	s_waitcnt lgkmcnt(0)
	v_add_f32_e32 v0, v0, v2
	ds_bpermute_b32 v2, v68, v1
	s_waitcnt lgkmcnt(0)
	v_add_f32_e32 v1, v1, v2
	v_xor_b32_e32 v2, 4, v226
	v_cmp_lt_i32_e32 vcc, v2, v162
	s_nop 1
	v_cndmask_b32_e32 v2, v226, v2, vcc
	v_lshlrev_b32_e32 v67, 2, v2
	ds_bpermute_b32 v2, v67, v0
	s_waitcnt lgkmcnt(0)
	v_add_f32_e32 v104, v0, v2
	ds_bpermute_b32 v0, v67, v1
	s_waitcnt lgkmcnt(0)
	v_add_f32_e32 v105, v1, v0
	v_xor_b32_e32 v0, 8, v226
	v_cmp_lt_i32_e32 vcc, v0, v162
	s_nop 1
	v_cndmask_b32_e32 v0, v226, v0, vcc
	v_lshlrev_b32_e32 v32, 2, v0
	v_add_co_u32_e32 v0, vcc, 0x15000, v6
	ds_bpermute_b32 v106, v32, v104
	s_nop 0
	v_addc_co_u32_e32 v1, vcc, 0, v7, vcc
	v_add_co_u32_e32 v0, vcc, 0x2a000, v6
	ds_bpermute_b32 v107, v32, v105
	s_nop 0
	v_addc_co_u32_e32 v1, vcc, 0, v7, vcc
	v_add_co_u32_e32 v0, vcc, 0x3f000, v6
	s_nop 1
	v_addc_co_u32_e32 v1, vcc, 0, v7, vcc
	s_nop 0
	s_nop 0
	s_cbranch_scc1 .LBB0_1183
	s_cmp_gt_i32 s65, 2
	s_cbranch_scc0 .LBB0_1180
	s_mov_b64 s[10:11], 0

.LBB0_1187:
	s_waitcnt lgkmcnt(1)
	v_add_f32_e32 v75, v104, v106
	v_mul_f32_e32 v73, 0x3b000000, v75
	s_waitcnt lgkmcnt(0)
	v_add_f32_e32 v72, v105, v107
	v_mul_f32_e32 v73, v73, v73
	v_fma_f32 v72, v72, s73, -v73
	v_max_f32_e32 v72, 0, v72
	v_add_f32_e32 v72, 0x358637bd, v72
	v_cmp_gt_f32_e32 vcc, s5, v72
	v_mul_f32_e32 v73, 0x4f800000, v72
	v_fmac_f32_e32 v103, 0xbb000000, v75
	v_cndmask_b32_e32 v72, v72, v73, vcc
	v_sqrt_f32_e32 v73, v72
	v_fmac_f32_e32 v102, 0xbb000000, v75
	v_fmac_f32_e32 v101, 0xbb000000, v75
	v_fmac_f32_e32 v100, 0xbb000000, v75
	v_add_u32_e32 v74, -1, v73
	v_fma_f32 v76, -v74, v73, v72
	v_cmp_ge_f32_e64 s[10:11], 0, v76
	v_add_u32_e32 v76, 1, v73
	v_fmac_f32_e32 v99, 0xbb000000, v75
	v_cndmask_b32_e64 v74, v73, v74, s[10:11]
	v_fma_f32 v73, -v76, v73, v72
	v_cmp_lt_f32_e64 s[10:11], 0, v73
	v_fmac_f32_e32 v98, 0xbb000000, v75
	v_or_b32_e32 v70, s31, v66
	v_cndmask_b32_e64 v73, v74, v76, s[10:11]
	v_mul_f32_e32 v74, 0x37800000, v73
	v_cndmask_b32_e32 v73, v73, v74, vcc
	v_cmp_class_f32_e32 vcc, v72, v220
	v_fmac_f32_e32 v96, 0xbb000000, v75
	v_lshl_add_u32 v71, v89, 4, 0
	v_cndmask_b32_e32 v72, v73, v72, vcc
	v_div_scale_f32 v73, s[8:9], v72, v72, 1.0
	v_rcp_f32_e32 v74, v73
	s_movk_i32 s8, 0x120
	v_fmac_f32_e32 v97, 0xbb000000, v75
	v_mul_lo_u32 v70, v70, s8
	v_fma_f32 v76, -v73, v74, 1.0
	v_fmac_f32_e32 v74, v76, v74
	v_div_scale_f32 v76, vcc, 1.0, v72, 1.0
	v_mul_f32_e32 v77, v76, v74
	v_fma_f32 v78, -v73, v77, v76
	v_fmac_f32_e32 v77, v78, v74
	v_fma_f32 v73, -v73, v77, v76
	v_div_fmas_f32 v73, v73, v74, v77
	v_div_fixup_f32 v76, v73, v72, 1.0
	v_mul_f32_e32 v72, v76, v103
	v_mul_f32_e32 v73, v76, v102
	s_waitcnt vmcnt(21)
	v_mov_b64_e32 v[16:17], v[118:119]
	v_mov_b64_e32 v[18:19], v[120:121]
	v_mov_b64_e32 v[0:1], v[124:125]
	v_mov_b64_e32 v[2:3], v[126:127]
	v_mov_b64_e32 v[8:9], v[128:129]
	v_mov_b64_e32 v[10:11], v[130:131]
	v_mov_b64_e32 v[4:5], v[132:133]
	v_mov_b64_e32 v[6:7], v[134:135]
	v_mov_b64_e32 v[12:13], v[136:137]
	v_mov_b64_e32 v[14:15], v[138:139]
	v_fma_f32 v72, v8, v72, v12
	v_fma_f32 v73, v9, v73, v13
	v_cvt_pk_bf16_f32 v72, v72, v73
	v_mul_f32_e32 v73, v76, v101
	v_mul_f32_e32 v74, v76, v100
	v_fma_f32 v73, v10, v73, v14
	v_fma_f32 v74, v11, v74, v15
	v_cvt_pk_bf16_f32 v73, v73, v74
	v_mul_f32_e32 v74, v76, v99
	v_mul_f32_e32 v77, v76, v98
	v_fma_f32 v74, v0, v74, v4
	v_fma_f32 v77, v1, v77, v5
	v_mul_f32_e32 v75, v76, v96
	v_cvt_pk_bf16_f32 v74, v74, v77
	v_mul_f32_e32 v77, v76, v97
	v_fma_f32 v75, v3, v75, v7
	v_add_u32_e32 v70, v71, v70
	v_fma_f32 v77, v2, v77, v6
	v_cvt_pk_bf16_f32 v75, v77, v75
	ds_write_b128 v70, v[72:75]
	v_lshlrev_b32_e32 v71, 16, v62
	v_and_b32_e32 v62, 0xffff0000, v62
	v_lshlrev_b32_e32 v72, 16, v63
	v_and_b32_e32 v63, 0xffff0000, v63
	v_lshlrev_b32_e32 v73, 16, v64
	v_and_b32_e32 v64, 0xffff0000, v64
	v_lshlrev_b32_e32 v74, 16, v65
	v_and_b32_e32 v65, 0xffff0000, v65
	v_add_f32_e32 v75, v71, v62
	v_add_f32_e32 v76, v72, v63
	v_add_f32_e32 v75, v75, v76
	v_add_f32_e32 v76, v73, v64
	v_add_f32_e32 v77, v74, v65
	v_add_f32_e32 v76, v76, v77
	v_add_f32_e32 v75, v75, v76
	v_add_f32_e32 v79, 0, v75
	v_mul_f32_e32 v75, v62, v62
	v_mul_f32_e32 v76, v63, v63
	v_fmac_f32_e32 v75, v71, v71
	v_fmac_f32_e32 v76, v72, v72
	v_add_f32_e32 v75, v75, v76
	v_mul_f32_e32 v76, v64, v64
	v_mul_f32_e32 v77, v65, v65
	v_fmac_f32_e32 v76, v73, v73
	v_fmac_f32_e32 v77, v74, v74
	v_add_f32_e32 v76, v76, v77
	v_add_f32_e32 v80, v75, v76
	v_lshlrev_b32_e32 v75, 16, v58
	v_and_b32_e32 v58, 0xffff0000, v58
	v_lshlrev_b32_e32 v76, 16, v59
	v_and_b32_e32 v59, 0xffff0000, v59
	v_lshlrev_b32_e32 v77, 16, v60
	v_and_b32_e32 v60, 0xffff0000, v60
	v_lshlrev_b32_e32 v78, 16, v61
	v_and_b32_e32 v61, 0xffff0000, v61
	v_add_f32_e32 v81, v75, v58
	v_add_f32_e32 v82, v76, v59
	v_add_f32_e32 v81, v81, v82
	v_add_f32_e32 v82, v77, v60
	v_add_f32_e32 v83, v78, v61
	v_add_f32_e32 v82, v82, v83
	v_add_f32_e32 v81, v81, v82
	v_add_f32_e32 v79, v79, v81
	v_mul_f32_e32 v81, v58, v58
	v_mul_f32_e32 v82, v59, v59
	v_fmac_f32_e32 v81, v75, v75
	v_fmac_f32_e32 v82, v76, v76
	v_add_f32_e32 v81, v81, v82
	v_mul_f32_e32 v82, v60, v60
	v_mul_f32_e32 v83, v61, v61
	v_fmac_f32_e32 v82, v77, v77
	v_fmac_f32_e32 v83, v78, v78
	v_add_f32_e32 v82, v82, v83
	v_add_f32_e32 v81, v81, v82
	v_add_f32_e32 v90, v80, v81
	v_lshlrev_b32_e32 v80, 16, v54
	v_and_b32_e32 v81, 0xffff0000, v54
	v_lshlrev_b32_e32 v82, 16, v55
	v_and_b32_e32 v83, 0xffff0000, v55
	v_lshlrev_b32_e32 v84, 16, v56
	v_and_b32_e32 v85, 0xffff0000, v56
	v_lshlrev_b32_e32 v86, 16, v57
	v_and_b32_e32 v87, 0xffff0000, v57
	v_add_f32_e32 v54, v80, v81
	v_add_f32_e32 v55, v82, v83
	v_add_f32_e32 v54, v54, v55
	v_add_f32_e32 v55, v84, v85
	v_add_f32_e32 v56, v86, v87
	v_add_f32_e32 v55, v55, v56
	v_add_f32_e32 v54, v54, v55
	v_add_f32_e32 v91, v79, v54
	v_mul_f32_e32 v54, v81, v81
	v_mul_f32_e32 v55, v83, v83
	v_fmac_f32_e32 v54, v80, v80
	v_fmac_f32_e32 v55, v82, v82
	v_add_f32_e32 v54, v54, v55
	v_mul_f32_e32 v55, v85, v85
	v_mul_f32_e32 v56, v87, v87
	v_fmac_f32_e32 v55, v84, v84
	v_fmac_f32_e32 v56, v86, v86
	v_add_f32_e32 v55, v55, v56
	v_add_f32_e32 v54, v54, v55
	v_lshlrev_b32_e32 v79, 16, v50
	v_and_b32_e32 v57, 0xffff0000, v50
	v_lshlrev_b32_e32 v56, 16, v51
	v_and_b32_e32 v55, 0xffff0000, v51
	v_add_f32_e32 v90, v90, v54
	v_lshlrev_b32_e32 v54, 16, v52
	v_and_b32_e32 v52, 0xffff0000, v52
	v_lshlrev_b32_e32 v51, 16, v53
	v_and_b32_e32 v50, 0xffff0000, v53
	v_add_f32_e32 v53, v79, v57
	v_add_f32_e32 v92, v56, v55
	v_add_f32_e32 v53, v53, v92
	v_add_f32_e32 v92, v54, v52
	v_add_f32_e32 v93, v51, v50
	v_add_f32_e32 v92, v92, v93
	v_add_f32_e32 v53, v53, v92
	v_add_f32_e32 v53, v91, v53
	v_mul_f32_e32 v91, v57, v57
	v_mul_f32_e32 v92, v55, v55
	v_fmac_f32_e32 v91, v79, v79
	v_fmac_f32_e32 v92, v56, v56
	v_add_f32_e32 v91, v91, v92
	v_mul_f32_e32 v92, v52, v52
	v_mul_f32_e32 v93, v50, v50
	v_fmac_f32_e32 v92, v54, v54
	v_fmac_f32_e32 v93, v51, v51
	v_add_f32_e32 v92, v92, v93
	v_add_f32_e32 v91, v91, v92
	v_add_f32_e32 v90, v90, v91
	ds_bpermute_b32 v91, v69, v53
	s_cmp_lt_i32 s65, 2
	s_mov_b64 s[10:11], -1
	s_waitcnt lgkmcnt(0)
	v_add_f32_e32 v53, v53, v91
	ds_bpermute_b32 v91, v69, v90
	s_waitcnt lgkmcnt(0)
	v_add_f32_e32 v90, v90, v91
	ds_bpermute_b32 v91, v68, v53
	s_waitcnt lgkmcnt(0)
	v_add_f32_e32 v53, v53, v91
	ds_bpermute_b32 v91, v68, v90
	s_waitcnt lgkmcnt(0)
	v_add_f32_e32 v90, v90, v91
	ds_bpermute_b32 v91, v67, v53
	s_waitcnt lgkmcnt(0)
	v_add_f32_e32 v53, v53, v91
	ds_bpermute_b32 v91, v67, v90
	s_waitcnt lgkmcnt(0)
	v_add_f32_e32 v90, v90, v91
	ds_bpermute_b32 v91, v32, v53
	ds_bpermute_b32 v92, v32, v90
	s_cbranch_scc1 .LBB0_1191
	s_cmp_lt_i32 s65, 3
	s_cbranch_scc0 .LBB0_1190
	v_mov_b32_e32 v79, v80
	v_mov_b32_e32 v57, v81
	v_mov_b32_e32 v56, v82
	v_mov_b32_e32 v55, v83
	v_mov_b32_e32 v54, v84
	v_mov_b32_e32 v52, v85
	v_mov_b32_e32 v51, v86
	v_mov_b32_e32 v50, v87

.LBB0_1217:
	s_waitcnt lgkmcnt(1)
	v_add_f32_e32 v19, v19, v52
	v_mul_f32_e32 v25, 0x3b000000, v19
	s_waitcnt lgkmcnt(0)
	v_add_f32_e32 v24, v51, v32
	v_mul_f32_e32 v25, v25, v25
	v_fma_f32 v24, v24, s73, -v25
	v_max_f32_e32 v24, 0, v24
	v_add_f32_e32 v24, 0x358637bd, v24
	v_cmp_gt_f32_e32 vcc, s5, v24
	v_mul_f32_e32 v25, 0x4f800000, v24
	v_fmac_f32_e32 v43, 0xbb000000, v19
	v_cndmask_b32_e32 v24, v24, v25, vcc
	v_sqrt_f32_e32 v25, v24
	v_fmac_f32_e32 v23, 0xbb000000, v19
	v_fmac_f32_e32 v22, 0xbb000000, v19
	v_fmac_f32_e32 v21, 0xbb000000, v19
	v_add_u32_e32 v26, -1, v25
	v_fma_f32 v27, -v26, v25, v24
	v_cmp_ge_f32_e64 s[10:11], 0, v27
	v_add_u32_e32 v27, 1, v25
	v_fmac_f32_e32 v20, 0xbb000000, v19
	v_cndmask_b32_e64 v26, v25, v26, s[10:11]
	v_fma_f32 v25, -v27, v25, v24
	v_cmp_lt_f32_e64 s[10:11], 0, v25
	v_fmac_f32_e32 v18, 0xbb000000, v19
	v_fmac_f32_e32 v17, 0xbb000000, v19
	v_cndmask_b32_e64 v25, v26, v27, s[10:11]
	v_mul_f32_e32 v26, 0x37800000, v25
	v_cndmask_b32_e32 v25, v25, v26, vcc
	v_cmp_class_f32_e32 vcc, v24, v220
	v_fmac_f32_e32 v16, 0xbb000000, v19
	v_lshlrev_b32_e32 v32, 3, v66
	v_cndmask_b32_e32 v24, v25, v24, vcc
	v_div_scale_f32 v25, s[8:9], v24, v24, 1.0
	v_rcp_f32_e32 v26, v25
	v_readlane_b32 s48, v252, 36
	v_readlane_b32 s62, v252, 50
	v_readlane_b32 s63, v252, 51
	v_fma_f32 v27, -v25, v26, 1.0
	v_fmac_f32_e32 v26, v27, v26
	v_div_scale_f32 v27, vcc, 1.0, v24, 1.0
	v_mul_f32_e32 v28, v27, v26
	v_fma_f32 v29, -v25, v28, v27
	v_fmac_f32_e32 v28, v29, v26
	v_fma_f32 v25, -v25, v28, v27
	v_div_fmas_f32 v25, v25, v26, v28
	v_div_fixup_f32 v24, v25, v24, 1.0
	v_mul_f32_e32 v25, v24, v43
	v_fma_f32 v8, v8, v25, v12
	v_mul_f32_e32 v12, v24, v23
	v_fma_f32 v9, v9, v12, v13
	v_cvt_pk_bf16_f32 v8, v8, v9
	v_mul_f32_e32 v9, v24, v22
	v_fma_f32 v9, v10, v9, v14
	v_mul_f32_e32 v10, v24, v21
	v_fmac_f32_e32 v15, v11, v10
	v_mul_f32_e32 v10, v24, v20
	v_fma_f32 v0, v0, v10, v4
	v_mul_f32_e32 v4, v24, v18
	v_fma_f32 v1, v1, v4, v5
	v_cvt_pk_bf16_f32 v10, v0, v1
	v_mul_f32_e32 v0, v24, v17
	v_mul_f32_e32 v1, v24, v16
	v_or_b32_e32 v4, s31, v89
	v_fma_f32 v0, v2, v0, v6
	v_fmac_f32_e32 v7, v3, v1
	v_ashrrev_i32_e32 v5, 31, v4
	v_cvt_pk_bf16_f32 v11, v0, v7
	v_lshlrev_b64 v[0:1], 8, v[4:5]
	v_add_u32_e32 v5, s30, v4
	v_mov_b64_e32 v[6:7], s[34:35]
	v_lshl_add_u64 v[0:1], s[18:19], 0, v[0:1]
	v_lshlrev_b32_e32 v2, 4, v66
	v_mov_b32_e32 v3, v33
	v_mad_i64_i32 v[6:7], s[8:9], v5, s70, v[6:7]
	v_cvt_pk_bf16_f32 v9, v9, v15
	ds_write_b128 v70, v[8:11] offset:3456
	v_lshl_add_u64 v[0:1], v[0:1], 0, v[2:3]
	v_lshl_add_u64 v[54:55], v[6:7], 0, v[32:33]
	s_nop 0
	s_nop 0
	v_add_u32_e32 v4, s2, v4
	v_ashrrev_i32_e32 v5, 31, v4
	v_lshl_add_u64 v[4:5], v[4:5], 2, s[62:63]
	s_waitcnt vmcnt(0)
	v_mov_b64_e32 v[50:51], v[140:141]
	v_mov_b64_e32 v[52:53], v[142:143]
	v_mov_b64_e32 v[46:47], v[144:145]
	v_mov_b64_e32 v[48:49], v[146:147]
	v_mov_b64_e32 v[38:39], v[148:149]
	v_mov_b64_e32 v[40:41], v[150:151]
	v_mov_b64_e32 v[0:1], v[152:153]
	v_mov_b64_e32 v[2:3], v[154:155]
	v_mov_b64_e32 v[86:87], v[164:165]
	v_mov_b64_e32 v[84:85], v[166:167]
	v_mov_b64_e32 v[82:83], v[168:169]
	v_mov_b64_e32 v[80:81], v[170:171]
	v_mov_b64_e32 v[78:79], v[172:173]
	v_mov_b64_e32 v[76:77], v[174:175]
	v_mov_b64_e32 v[72:73], v[176:177]
	v_mov_b64_e32 v[74:75], v[178:179]
	v_mov_b64_e32 v[70:71], v[180:181]
	v_mov_b64_e32 v[68:69], v[182:183]
	v_mov_b64_e32 v[66:67], v[184:185]
	v_mov_b64_e32 v[64:65], v[186:187]
	v_mov_b64_e32 v[62:63], v[188:189]
	v_mov_b64_e32 v[60:61], v[190:191]
	v_mov_b64_e32 v[56:57], v[192:193]
	v_mov_b64_e32 v[58:59], v[194:195]
	v_mov_b32_e32 v90, v156
	v_lshrrev_b32_e32 v4, 2, v89
	v_or_b32_e32 v4, v32, v4
	v_lshlrev_b32_e32 v5, 3, v88
	v_mov_b32_e32 v42, 0
	s_ashr_i32 s8, s28, 7
	v_mul_u32_u24_e32 v4, 0x120, v4
	v_and_b32_e32 v5, 24, v5
	v_add3_u32 v32, 0, v4, v5
	s_cmp_lt_i32 s8, 0
	v_mov_b32_e32 v43, 0
	v_mov_b32_e32 v44, 0
	v_mov_b32_e32 v45, 0
	v_mov_b32_e32 v28, 0
	v_mov_b32_e32 v29, v42
	v_mov_b32_e32 v30, v42
	v_mov_b32_e32 v31, v42
	v_mov_b32_e32 v24, v42
	v_mov_b32_e32 v25, v42
	v_mov_b32_e32 v26, v42
	v_mov_b32_e32 v27, v42
	v_mov_b32_e32 v20, v42
	v_mov_b32_e32 v21, v42
	v_mov_b32_e32 v22, v42
	v_mov_b32_e32 v23, v42
	v_mov_b32_e32 v16, v42
	v_mov_b32_e32 v17, v42
	v_mov_b32_e32 v18, v42
	v_mov_b32_e32 v19, v42
	v_mov_b32_e32 v12, v42
	v_mov_b32_e32 v13, v42
	v_mov_b32_e32 v14, v42
	v_mov_b32_e32 v15, v42
	v_mov_b32_e32 v8, v42
	v_mov_b32_e32 v9, v42
	v_mov_b32_e32 v10, v42
	v_mov_b32_e32 v11, v42
	v_mov_b32_e32 v4, v42
	v_mov_b32_e32 v5, v42
	v_mov_b32_e32 v6, v42
	v_mov_b32_e32 v7, v42
	v_mov_b32_e32 v34, v42
	v_mov_b32_e32 v35, v42
	v_mov_b32_e32 v36, v42
	v_mov_b32_e32 v37, v42
	v_readlane_b32 s49, v252, 37
	v_readlane_b32 s50, v252, 38
	v_readlane_b32 s51, v252, 39
	v_readlane_b32 s52, v252, 40
	v_readlane_b32 s53, v252, 41
	v_readlane_b32 s54, v252, 42
	v_readlane_b32 s55, v252, 43
	v_readlane_b32 s56, v252, 44
	v_readlane_b32 s57, v252, 45
	v_readlane_b32 s58, v252, 46
	v_readlane_b32 s59, v252, 47
	v_readlane_b32 s60, v252, 48
	v_readlane_b32 s61, v252, 49
	s_waitcnt lgkmcnt(0)
	s_barrier
	s_cbranch_scc0 .LBB0_1221
	s_cmp_lt_i32 s8, 1
	s_cbranch_scc0 .LBB0_1222
